# P9: partner wave of a heavy compressed-branch task runs heads 3-5 of its pass 1 instead of idling (LDS hand-over), on top of v12
# speedup vs baseline: 1.0020x; 1.0020x over previous
.LBB0_1059:
	s_cmp_lt_i32 s74, 10
	s_cselect_b64 s[0:1], -1, 0
	s_and_b64 s[40:41], s[0:1], s[2:3]
	s_andn2_b64 vcc, exec, s[40:41]
	s_cbranch_vccnz .LBB0_1203
	s_mov_b32 s101, 0
	s_mov_b32 s98, 0
	v_readlane_b32 s0, v254, 23
	v_lshlrev_b32_e32 v1, 2, v199
	v_readlane_b32 s6, v254, 29
	v_readlane_b32 s7, v254, 30
	v_readlane_b32 s12, v254, 35
	v_readlane_b32 s13, v254, 36
	s_nop 2
	global_load_dword v2, v1, s[6:7]
	s_waitcnt lgkmcnt(0)
	global_load_dword v3, v1, s[12:13]
	global_load_dword v4, v1, s[12:13] offset:512
	v_mbcnt_lo_u32_b32 v1, -1, 0
	v_mbcnt_hi_u32_b32 v1, -1, v1
	v_and_b32_e32 v5, 64, v1
	v_xor_b32_e32 v6, 1, v1
	v_add_u32_e32 v5, 64, v5
	v_cmp_lt_i32_e32 vcc, v6, v5
	v_xor_b32_e32 v7, 2, v1
	v_xor_b32_e32 v8, 4, v1
	v_cndmask_b32_e32 v6, v1, v6, vcc
	v_lshlrev_b32_e32 v6, 2, v6
	v_cmp_lt_i32_e32 vcc, v7, v5
	v_xor_b32_e32 v9, 8, v1
	v_xor_b32_e32 v10, 16, v1
	v_cndmask_b32_e32 v7, v1, v7, vcc
	v_lshlrev_b32_e32 v7, 2, v7
	v_cmp_lt_i32_e32 vcc, v8, v5
	v_xor_b32_e32 v11, 32, v1
	s_add_u32 s46, s72, 0x70000
	v_cndmask_b32_e32 v8, v1, v8, vcc
	v_lshlrev_b32_e32 v8, 2, v8
	v_cmp_lt_i32_e32 vcc, v9, v5
	s_addc_u32 s47, s73, 0
	s_cmpk_lt_u32 s76, 0x100
	v_cndmask_b32_e32 v9, v1, v9, vcc
	v_lshlrev_b32_e32 v9, 2, v9
	v_cmp_lt_i32_e32 vcc, v10, v5
	v_readlane_b32 s2, v254, 25
	v_readlane_b32 s3, v254, 26
	s_cselect_b64 s[50:51], -1, 0
	s_cmpk_gt_u32 s76, 0xff
	v_readlane_b32 s4, v254, 27
	s_cselect_b64 s[2:3], -1, 0
	s_mov_b32 s4, -1
	v_readlane_b32 s1, v254, 24
	v_readlane_b32 s5, v254, 28
	v_readlane_b32 s8, v254, 31
	v_readlane_b32 s9, v254, 32
	v_readlane_b32 s10, v254, 33
	v_readlane_b32 s11, v254, 34
	v_readlane_b32 s14, v254, 37
	v_readlane_b32 s15, v254, 38
	s_waitcnt vmcnt(0)
	v_and_b32_e32 v12, 0x7fffffff, v2
	v_and_b32_e32 v13, 0x7fffffff, v3
	v_and_b32_e32 v14, 0x7fffffff, v4
	ds_bpermute_b32 v12, v6, v12
	ds_bpermute_b32 v13, v6, v13
	ds_bpermute_b32 v6, v6, v14
	v_max_f32_e64 v2, |v2|, |v2|
	v_max_f32_e64 v3, |v3|, |v3|
	v_max_f32_e64 v4, |v4|, |v4|
	s_waitcnt lgkmcnt(2)
	v_max_f32_e32 v12, v12, v12
	s_waitcnt lgkmcnt(1)
	v_max_f32_e32 v13, v13, v13
	s_waitcnt lgkmcnt(0)
	v_max_f32_e32 v6, v6, v6
	v_max_f32_e32 v2, v2, v12
	v_max_f32_e32 v3, v3, v13
	v_max_f32_e32 v4, v4, v6
	ds_bpermute_b32 v6, v7, v2
	ds_bpermute_b32 v12, v7, v3
	ds_bpermute_b32 v7, v7, v4
	s_waitcnt lgkmcnt(2)
	v_max_f32_e32 v6, v6, v6
	s_waitcnt lgkmcnt(1)
	v_max_f32_e32 v12, v12, v12
	s_waitcnt lgkmcnt(0)
	v_max_f32_e32 v7, v7, v7
	v_max_f32_e32 v2, v2, v6
	v_max_f32_e32 v3, v3, v12
	v_max_f32_e32 v4, v4, v7
	ds_bpermute_b32 v6, v8, v2
	ds_bpermute_b32 v7, v8, v3
	ds_bpermute_b32 v8, v8, v4
	s_waitcnt lgkmcnt(2)
	v_max_f32_e32 v6, v6, v6
	s_waitcnt lgkmcnt(1)
	v_max_f32_e32 v7, v7, v7
	s_waitcnt lgkmcnt(0)
	v_max_f32_e32 v8, v8, v8
	v_max_f32_e32 v2, v2, v6
	v_max_f32_e32 v3, v3, v7
	v_max_f32_e32 v4, v4, v8
	ds_bpermute_b32 v6, v9, v2
	ds_bpermute_b32 v7, v9, v3
	ds_bpermute_b32 v8, v9, v4
	v_cndmask_b32_e32 v9, v1, v10, vcc
	v_lshlrev_b32_e32 v9, 2, v9
	s_waitcnt lgkmcnt(2)
	v_max_f32_e32 v6, v6, v6
	s_waitcnt lgkmcnt(1)
	v_max_f32_e32 v7, v7, v7
	s_waitcnt lgkmcnt(0)
	v_max_f32_e32 v8, v8, v8
	v_max_f32_e32 v2, v2, v6
	v_max_f32_e32 v3, v3, v7
	v_max_f32_e32 v4, v4, v8
	ds_bpermute_b32 v6, v9, v2
	ds_bpermute_b32 v7, v9, v3
	ds_bpermute_b32 v8, v9, v4
	v_cmp_lt_i32_e32 vcc, v11, v5
	s_waitcnt lgkmcnt(1)
	v_max_f32_e32 v5, v7, v7
	v_cndmask_b32_e32 v1, v1, v11, vcc
	v_lshlrev_b32_e32 v207, 2, v1
	v_max_f32_e32 v1, v6, v6
	s_waitcnt lgkmcnt(0)
	v_max_f32_e32 v6, v8, v8
	v_max_f32_e32 v2, v2, v1
	v_max_f32_e32 v1, v3, v5
	v_max_f32_e32 v181, v4, v6
	ds_bpermute_b32 v4, v207, v2
	ds_bpermute_b32 v3, v207, v1
	ds_bpermute_b32 v204, v207, v181
	s_and_b64 vcc, exec, s[2:3]
	s_cbranch_vccnz .LBB0_1068
	v_cmp_eq_u32_e32 vcc, 0, v199
	v_mov_b32_e32 v5, -1
	s_and_saveexec_b64 s[4:5], vcc
	s_cbranch_execz .LBB0_1065
	s_mov_b64 s[8:9], exec
	v_mbcnt_lo_u32_b32 v5, s8, 0
	v_mbcnt_hi_u32_b32 v5, s9, v5
	v_cmp_eq_u32_e64 s[0:1], 0, v5
	s_and_saveexec_b64 s[6:7], s[0:1]
	s_cbranch_execz .LBB0_1064
	s_bcnt1_i32_b64 s0, s[8:9]
	v_mov_b32_e32 v6, 0
	v_mov_b32_e32 v7, s0
	global_atomic_add v6, v6, v7, s[46:47] sc0

.LBB0_1065:
	s_or_b64 exec, exec, s[4:5]
	v_readfirstlane_b32 s4, v5
	s_and_saveexec_b64 s[0:1], vcc
	s_cbranch_execz .LBB0_1067
	s_lshl_b32 s5, s77, 2
	s_add_i32 s5, s5, 0
	s_add_i32 s5, s5, 0x1d4c0
	s_add_i32 s7, s4, 1
	s_cmpk_lt_u32 s4, 0x1c0
	s_cselect_b32 s6, s7, 0
	v_mov_b32_e32 v5, s6
	v_mov_b32_e32 v6, s5
	v_mov_b32_e32 v7, 0
	ds_write_b32 v6, v5
	ds_write_b32 v6, v7 offset:32

.LBB0_1068:
	s_waitcnt lgkmcnt(2)
	v_max_f32_e32 v4, v4, v4
	v_max_f32_e32 v2, v2, v2
	v_max_f32_e32 v2, v2, v4
	v_mul_f32_e32 v205, 0x4138aa3b, v2
	s_waitcnt lgkmcnt(1)
	v_max_f32_e32 v2, v3, v3
	v_max_f32_e32 v1, v1, v1
	v_max_f32_e32 v1, v1, v2
	v_mul_f32_e32 v1, v205, v1
	s_lshl_b32 s5, s77, 10
	s_andn2_b64 vcc, exec, s[2:3]
	s_mov_b64 s[0:1], -1
	s_waitcnt lgkmcnt(0)
	s_barrier
	s_cbranch_vccnz .LBB0_1074
	s_lshl_b32 s0, s77, 2
	s_add_i32 s0, s0, 0
	s_add_i32 s0, s0, 0x1d4b0
	v_mov_b32_e32 v2, s0
	ds_read_b32 v3, v2
	s_waitcnt lgkmcnt(0)
	v_readfirstlane_b32 s0, v3
	s_cmp_eq_u32 s0, 0
	s_cbranch_scc1 .LBB0_1073
	s_add_i32 s4, s0, -1
	s_mov_b32 s101, 1
	s_mov_b32 s98, 1
	s_mov_b64 s[0:1], -1
	s_branch .LBB0_1074

.LBB0_1074:
	v_mul_f32_e32 v224, 0x3f828f5c, v1
	s_add_i32 s12, s5, 0
	s_lshl_b32 s100, s101, 12
	s_sub_i32 s12, s12, s100
	s_and_b64 vcc, exec, s[0:1]
	s_cbranch_vccz .LBB0_1127
	s_cmpk_gt_u32 s4, 0x3ff
	s_cbranch_scc1 .LBB0_1124
	s_cmp_eq_u32 s101, 1
	s_cbranch_scc1 .Lp9_role_set
	s_cmpk_lt_u32 s4, 0x1c0
	s_cselect_b32 s98, 1, 0
.Lp9_role_set:
	s_lshr_b32 s0, s4, 1
	s_sub_i32 s2, 0x1ff, s0
	v_and_b32_e32 v1, 31, v198
	s_lshl_b32 s3, s2, 5
	v_or_b32_e32 v166, s3, v1
	v_subrev_u32_e32 v2, 31, v166
	s_lshl_b32 s2, s2, 1
	v_lshrrev_b32_e32 v2, 4, v2
	s_add_i32 s2, s2, 32
	s_and_b32 s8, s4, 1
	v_add_u32_e32 v2, 1, v2
	v_cmp_lt_u32_e32 vcc, 30, v166
	s_lshr_b32 s13, s2, 5
	s_sub_i32 s2, s3, 31
	v_cndmask_b32_e32 v164, 0, v2, vcc
	s_ashr_i32 s10, s2, 4
	s_lshl_b32 s2, s8, 17
	v_mov_b32_e32 v2, 0x180
	s_add_u32 s2, s72, s2
	v_mul_u32_u24_e32 v2, s8, v2
	s_addc_u32 s3, s73, 0
	v_mul_hi_u32_u24_e32 v5, 0x300, v166
	v_mul_u32_u24_e32 v4, 0x300, v166
	v_lshlrev_b32_e32 v6, 1, v2
	v_mov_b32_e32 v2, 0
	v_lshrrev_b32_e32 v3, 5, v199
	s_add_u32 s52, s2, 0x100000
	v_mov_b32_e32 v7, v2
	v_lshl_add_u64 v[4:5], v[4:5], 1, s[72:73]
	s_addc_u32 s53, s3, 0
	v_lshlrev_b32_e32 v10, 4, v3
	v_mov_b32_e32 v11, v2
	v_lshl_add_u64 v[4:5], v[4:5], 0, v[6:7]
	s_add_u32 s2, s2, 0x140000
	v_lshl_add_u64 v[6:7], v[4:5], 0, v[10:11]
	s_mov_b64 s[4:5], 0x9400000
	s_addc_u32 s3, s3, 0
	v_mov_b64_e32 v[12:13], s[72:73]
	v_lshl_add_u64 v[184:185], v[6:7], 0, s[4:5]
	s_movk_i32 s4, 0x90
	v_mul_u32_u24_e64 v10, s8, 18
	s_add_i32 s9, s13, -1
	v_mad_u64_u32 v[6:7], s[4:5], v166, s4, v[12:13]
	v_lshlrev_b32_e32 v10, 2, v10
	s_cmp_eq_u32 s13, 1
	v_lshl_add_u64 v[6:7], v[6:7], 0, v[10:11]
	s_mov_b64 s[4:5], 0xb400000
	s_cselect_b32 s6, 0, 0x1000
	v_lshl_add_u64 v[186:187], v[6:7], 0, s[4:5]
	s_add_u32 s4, s52, s6
	v_lshlrev_b32_e32 v10, 4, v199
	s_addc_u32 s5, s53, 0
	v_lshl_add_u64 v[190:191], s[4:5], 0, v[10:11]
	s_add_u32 s4, s2, s6
	s_addc_u32 s5, s3, 0
	v_lshl_add_u64 v[192:193], s[4:5], 0, v[10:11]
	s_min_u32 s4, s9, 2
	s_lshl_b32 s4, s4, 12
	s_and_b32 s6, s4, 0x2000
	s_add_u32 s5, s52, s6
	s_addc_u32 s7, s53, 0
	s_and_b32 s11, s4, 0x1000
	s_add_u32 s4, s5, s11
	s_addc_u32 s5, s7, 0
	s_add_u32 s6, s2, s6
	s_addc_u32 s7, s3, 0
	s_add_u32 s6, s6, s11
	s_addc_u32 s7, s7, 0
	v_lshl_add_u64 v[194:195], s[6:7], 0, v[10:11]
	s_sub_i32 s6, s10, 31
	v_lshlrev_b32_e32 v8, 3, v3
	v_mov_b32_e32 v9, v2
	s_cmpk_lg_i32 s0, 0x1ff
	v_lshl_add_u32 v167, v1, 2, s12
	v_lshlrev_b32_e32 v6, 3, v199
	s_cselect_b32 s42, s6, 0xffffffe0
	v_lshlrev_b32_e32 v1, 2, v3
	v_lshl_add_u64 v[4:5], v[4:5], 0, v[8:9]
	s_mov_b64 s[6:7], 0xda00000
	s_mov_b32 s1, 0
	v_lshl_add_u64 v[182:183], s[52:53], 0, v[10:11]
	v_lshl_add_u64 v[188:189], s[2:3], 0, v[10:11]
	v_lshl_add_u64 v[196:197], v[4:5], 0, s[6:7]
	v_or_b32_e32 v165, 2, v1
	v_or_b32_e32 v168, 3, v1
	v_or_b32_e32 v169, 8, v1
	v_or_b32_e32 v170, 9, v1
	v_or_b32_e32 v171, 10, v1
	v_or_b32_e32 v172, 11, v1
	v_or_b32_e32 v173, 16, v1
	v_or_b32_e32 v174, 17, v1
	v_or_b32_e32 v175, 18, v1
	v_or_b32_e32 v176, 19, v1
	v_or_b32_e32 v177, 24, v1
	v_or_b32_e32 v178, 25, v1
	v_or_b32_e32 v179, 26, v1
	v_or_b32_e32 v180, 27, v1
	v_lshlrev_b32_e32 v206, 1, v6
	s_mul_i32 s10, s101, 3
	s_add_i32 s99, s10, 3
	s_cmp_eq_u32 s98, 0
	s_cselect_b32 s99, 6, s99
	s_branch .LBB0_1078
.LBB0_1077:
	s_lshl_b32 s0, s0, 1
	v_lshl_add_u64 v[36:37], v[196:197], 0, s[0:1]
	s_mul_i32 s0, s10, 3
	v_lshl_add_u64 v[38:39], s[0:1], 2, v[186:187]
	global_load_dword v3, v[38:39], off
	ds_bpermute_b32 v38, v207, v208
	v_lshl_add_u32 v39, s10, 7, v167
	s_add_i32 s10, s10, 1
	s_cmp_eq_u32 s10, s99
	s_waitcnt lgkmcnt(0)
	v_add_f32_e32 v38, v208, v38
	v_div_scale_f32 v40, s[6:7], v38, v38, 1.0
	v_rcp_f32_e32 v41, v40
	v_div_scale_f32 v42, vcc, 1.0, v38, 1.0
	v_fma_f32 v43, -v40, v41, 1.0
	v_fmac_f32_e32 v41, v43, v41
	v_mul_f32_e32 v43, v42, v41
	v_fma_f32 v44, -v40, v43, v42
	v_fmac_f32_e32 v43, v44, v41
	v_fma_f32 v40, -v40, v43, v42
	v_div_fmas_f32 v40, v40, v41, v43
	v_div_fixup_f32 v40, v40, v38, 1.0
	v_cmp_lt_f32_e32 vcc, 0, v38
	s_nop 1
	v_cndmask_b32_e32 v38, 0, v40, vcc
	ds_write_b32 v39, v38
	s_waitcnt vmcnt(0)
	v_mul_f32_e32 v38, v3, v38
	v_pk_mul_f32 v[22:23], v[22:23], v[38:39] op_sel_hi:[1,0]
	v_pk_mul_f32 v[20:21], v[20:21], v[38:39] op_sel_hi:[1,0]
	v_pk_mul_f32 v[6:7], v[6:7], v[38:39] op_sel_hi:[1,0]
	v_pk_mul_f32 v[4:5], v[4:5], v[38:39] op_sel_hi:[1,0]
	v_pk_mul_f32 v[26:27], v[26:27], v[38:39] op_sel_hi:[1,0]
	v_pk_mul_f32 v[24:25], v[24:25], v[38:39] op_sel_hi:[1,0]
	v_pk_mul_f32 v[10:11], v[10:11], v[38:39] op_sel_hi:[1,0]
	v_pk_mul_f32 v[8:9], v[8:9], v[38:39] op_sel_hi:[1,0]
	v_pk_mul_f32 v[30:31], v[30:31], v[38:39] op_sel_hi:[1,0]
	v_pk_mul_f32 v[28:29], v[28:29], v[38:39] op_sel_hi:[1,0]
	v_pk_mul_f32 v[14:15], v[14:15], v[38:39] op_sel_hi:[1,0]
	v_pk_mul_f32 v[12:13], v[12:13], v[38:39] op_sel_hi:[1,0]
	v_pk_mul_f32 v[34:35], v[34:35], v[38:39] op_sel_hi:[1,0]
	v_pk_mul_f32 v[32:33], v[32:33], v[38:39] op_sel_hi:[1,0]
	v_pk_mul_f32 v[18:19], v[18:19], v[38:39] op_sel_hi:[1,0]
	v_pk_mul_f32 v[16:17], v[16:17], v[38:39] op_sel_hi:[1,0]
	v_cvt_pk_bf16_f32 v20, v20, v21
	v_cvt_pk_bf16_f32 v21, v22, v23
	v_cvt_pk_bf16_f32 v4, v4, v5
	v_cvt_pk_bf16_f32 v5, v6, v7
	v_cvt_pk_bf16_f32 v6, v24, v25
	v_cvt_pk_bf16_f32 v7, v26, v27
	v_cvt_pk_bf16_f32 v8, v8, v9
	v_cvt_pk_bf16_f32 v9, v10, v11
	v_cvt_pk_bf16_f32 v10, v28, v29
	v_cvt_pk_bf16_f32 v11, v30, v31
	v_cvt_pk_bf16_f32 v12, v12, v13
	v_cvt_pk_bf16_f32 v13, v14, v15
	v_cvt_pk_bf16_f32 v14, v32, v33
	v_cvt_pk_bf16_f32 v15, v34, v35
	v_cvt_pk_bf16_f32 v16, v16, v17
	v_cvt_pk_bf16_f32 v17, v18, v19
	global_store_dwordx2 v[36:37], v[20:21], off
	global_store_dwordx2 v[36:37], v[4:5], off offset:64
	global_store_dwordx2 v[36:37], v[6:7], off offset:16
	global_store_dwordx2 v[36:37], v[8:9], off offset:80
	global_store_dwordx2 v[36:37], v[10:11], off offset:32
	global_store_dwordx2 v[36:37], v[12:13], off offset:96
	global_store_dwordx2 v[36:37], v[14:15], off offset:48
	global_store_dwordx2 v[36:37], v[16:17], off offset:112
	s_cbranch_scc1 .LBB0_1097

.LBB0_1097:
	s_cmp_eq_u32 s98, 0
	s_cbranch_scc1 .Lp9_pass2
	s_waitcnt lgkmcnt(0)
	s_cmp_eq_u32 s101, 0
	s_cbranch_scc1 .Lp9_wait_partner
	s_lshl_b32 s0, s77, 2
	s_add_i32 s0, s0, 0x1d4d0
	v_mov_b32_e32 v2, s0
	v_mov_b32_e32 v3, 1
	ds_write_b32 v2, v3
	s_waitcnt vmcnt(0) lgkmcnt(0)
	s_branch .LBB0_1127
.Lp9_wait_partner:
	s_lshl_b32 s0, s77, 2
	s_add_i32 s0, s0, 0x1d4e0
	v_mov_b32_e32 v2, s0
.Lp9_spin:
	ds_read_b32 v3, v2
	s_waitcnt lgkmcnt(0)
	v_readfirstlane_b32 s0, v3
	s_cmp_eq_u32 s0, 0
	s_cbranch_scc0 .Lp9_pass2
	s_sleep 8
	s_branch .Lp9_spin
